# plus: retention in-projection GEMM unit order: 96 sample-row units form the partial last round
# baseline (speedup 1.0000x reference)
.LBB0_462:
	s_load_dwordx2 s[2:3], s[78:79], 0x2a8
	v_writelane_b32 v254, s78, 19
	s_waitcnt lgkmcnt(0)
	s_cmp_lt_i32 s2, 4
	s_cselect_b64 s[96:97], -1, 0
	s_and_b64 s[0:1], s[96:97], s[0:1]
	s_andn2_b64 vcc, exec, s[0:1]
	v_writelane_b32 v254, s79, 20
	s_cbranch_vccnz .LBB0_1657
	s_load_dword s30, s[78:79], 0x2b0
	v_readfirstlane_b32 s33, v248
	s_waitcnt lgkmcnt(0)
	v_cvt_f32_u32_e32 v1, s30
	s_sub_i32 s0, 0, s30
	v_rcp_iflag_f32_e32 v1, v1
	s_nop 0
	v_mul_f32_e32 v1, 0x4f7ffffe, v1
	v_cvt_u32_f32_e32 v1, v1
	s_nop 0
	v_readfirstlane_b32 s1, v1
	s_mul_i32 s0, s0, s1
	s_mul_hi_u32 s0, s1, s0
	s_add_i32 s1, s1, s0
	s_mul_hi_u32 s0, s76, s1
	s_mul_i32 s0, s0, s30
	s_sub_i32 s0, s76, s0
	s_sub_i32 s1, s0, s30
	s_cmp_ge_u32 s0, s30
	s_cselect_b32 s0, s1, s0
	s_sub_i32 s1, s0, s30
	s_cmp_ge_u32 s0, s30
	s_cselect_b32 s31, s1, s0
	s_cmpk_lt_i32 s31, 0x660
	s_cselect_b64 s[2:3], -1, 0
	s_cmpk_gt_i32 s31, 0x65f
	s_cbranch_scc1 .LBB0_465
	s_and_b32 s6, s31, 7
	s_lshr_b32 s0, s31, 3
	s_and_b32 s1, s0, 7
	s_lshl_b32 s6, s6, 3
	s_add_u32 s6, s6, s1
	s_lshr_b32 s0, s0, 3
	s_sub_u32 s1, s31, 0x600
	s_and_b32 s4, s1, 3
	s_add_u32 s4, s4, 64
	s_lshr_b32 s1, s1, 2
	s_cmp_lt_u32 s31, 0x600
	s_cselect_b32 s6, s6, s4
	s_cselect_b32 s0, s0, s1

.LBB0_471:
	s_add_i32 s38, s38, 1
	s_mul_i32 s4, s38, s43
	s_mul_hi_u32 s5, s38, s30
	s_add_i32 s5, s5, s4
	s_mul_i32 s4, s38, s30
	s_add_u32 s18, s4, s31
	s_addc_u32 s19, s5, s44
	v_cmp_gt_i64_e64 s[4:5], s[18:19], v[142:143]
	s_and_b64 vcc, exec, s[4:5]
	s_cbranch_vccnz .LBB0_473
	s_and_b32 s16, s18, 7
	s_lshr_b32 s8, s18, 3
	s_and_b32 s7, s8, 7
	s_lshl_b32 s16, s16, 3
	s_add_u32 s16, s16, s7
	s_lshr_b32 s8, s8, 3
	s_sub_u32 s7, s18, 0x600
	s_and_b32 s9, s7, 3
	s_add_u32 s9, s9, 64
	s_lshr_b32 s7, s7, 2
	s_cmp_lt_u32 s18, 0x600
	s_cselect_b32 s16, s16, s9
	s_cselect_b32 s8, s8, s7
